# GLA group B two-stage landing: loader publishes the first 8 key fragments via a counted vmcnt, compute checks the full-landed flag just before fragment 8
# baseline (speedup 1.0000x reference)
; #define LAS __attribute__((address_space(3)))
; __device__ __forceinline__ void scan_loader(const P& p, int id, int role, LAS unsigned char* ldsw, int lane) {
;     volatile LAS unsigned* FL = (volatile LAS unsigned*)(ldsw + SCAN_FLAGS_OFF);
;     const int r = lane & 31, hh = lane >> 5;
;     const bool gla = id < 64; const int q = gla ? id : id - 64;
;     const int s = q >> 5, h = gla ? (q >> 3) & 3 : (q >> 2) & 7, sl = gla ? q & 7 : q & 3;
;     LAS unsigned char* bufA = ldsw + 16384; LAS unsigned char* bufB = ldsw + 16384 + (gla ? 28 : 40) * 1024;
; #pragma unroll 1
;     for (int n = 0; n < NCH; ++n) {
;         const int ch = gla ? (s * 64 + n) * 4 + h : (s * 64 + n) * 8 + h;
;         if (!lds_wait_ge<true>(FL + (role < 2 ? 3 : 4), (unsigned)n, FL + 5)) break;
;         if (role < 2) { if (gla) gla_issue_A_half(p, ch, sl, bufA, r, hh, role); else delta_issue_A_half(p, ch, sl, bufA, r, hh, role); }
;         else { if (gla) gla_issue_B(p, ch, bufB, r, hh); else delta_issue_B(p, ch, bufB, r, hh); }
.LBB0_1444:
	s_cmp_lt_i32 s37, 64
	s_cselect_b64 s[8:9], -1, 0
	s_cmp_gt_i32 s37, 63
	s_cselect_b64 s[6:7], -1, 0
	s_mov_b64 s[10:11], -1
	s_and_b64 vcc, exec, s[24:25]
	s_cbranch_vccz .LBB0_1476
	s_sub_i32 s10, s37, 64
	s_and_b64 s[4:5], s[8:9], exec
	s_cselect_b32 s10, s37, s10
	s_ashr_i32 s11, s10, 5
	s_bfe_u32 s12, s10, 0x20003
	s_bfe_u32 s13, s10, 0x30002
	s_and_b64 s[4:5], s[8:9], exec
	s_movk_i32 s4, 0x7000
	s_cselect_b32 s4, s4, 0xa000
	s_cselect_b32 s5, 7, 3
	s_and_b32 s5, s10, s5
	s_add_i32 s34, s4, 0
	s_lshl_b32 s4, s11, 9
	s_or_b32 s42, s4, s13
	s_lshl_b32 s4, s11, 8
	v_lshl_or_b32 v162, s5, 13, v139
	v_lshl_or_b32 v4, s5, 12, v142
	v_mov_b32_e32 v5, v163
	s_mov_b64 s[72:73], s[24:25]
	s_mov_b32 s63, s54
	s_or_b32 s43, s4, s12
	s_add_i32 s44, s34, 0x9c00
	s_add_i32 s45, s34, 0xbc00
	v_lshl_add_u64 v[2:3], v[182:183], 0, v[162:163]
	v_lshl_add_u64 v[4:5], v[184:185], 0, v[4:5]
	s_mov_b32 s46, 0
	s_add_i32 s47, s34, 0x4400
	s_add_i32 s48, s34, 0x4800
	s_add_i32 s49, s34, 0x4c00
	s_add_i32 s55, s34, 0x5400
	s_add_i32 s56, s34, 0x5800
	s_add_i32 s57, s34, 0x5c00
	s_add_i32 s92, s34, 0x6400
	s_add_i32 s93, s34, 0x6800
	s_add_i32 s96, s34, 0x6c00
	s_add_i32 s97, s34, 0x7400
	s_add_i32 s54, s34, 0x7800
	s_add_i32 s16, s34, 0x7c00
	s_add_i32 s4, s34, 0x8400
	s_add_i32 s5, s34, 0x8800
	s_add_i32 s24, s34, 0x8c00
	s_add_i32 s25, s34, 0x9400
	s_add_i32 s26, s34, 0x9800
	s_add_i32 s27, s34, 0xa400
	s_add_i32 s28, s34, 0xa800
	s_add_i32 s29, s34, 0xac00
	s_add_i32 s30, s34, 0xb000
	s_add_i32 s31, s34, 0xb400
	s_add_i32 s95, s34, 0xb800
	s_mov_b32 s101, 0
	s_cmp_lt_i32 s37, 64
	s_cbranch_scc0 .Lglb_cfg_done
	s_cmp_eq_u32 s17, 16
	s_cbranch_scc0 .Lglb_cfg_done
	s_mov_b32 s101, 1
.Lglb_cfg_done:
	s_branch .LBB0_1448

; #define VM_WAIT_N(n) asm volatile("s_waitcnt vmcnt(" #n ")" ::: "memory")
; __device__ __forceinline__ void scan_loader(const P& p, int id, int role, LAS unsigned char* ldsw, int lane) {
;     ...
;         else { if (gla) gla_issue_B(p, ch, bufB, r, hh); else delta_issue_B(p, ch, bufB, r, hh); }
;         VM_WAIT_N(0);
;         if (lane == 0) FL[role] = (unsigned)n + 1u;
.LBB0_1473:
	s_mov_b32 m0, s9
	s_add_i32 s46, s46, 1
	global_load_lds_dwordx4 v[6:7], off
	s_cmp_eq_u32 s101, 0
	s_cbranch_scc1 .Lglb_pub_skip
	s_waitcnt vmcnt(24)
	s_and_saveexec_b64 s[8:9], s[0:1]
	v_mov_b32_e32 v255, s46
	ds_write_b32 v163, v255 offset:13344
	s_or_b64 exec, exec, s[8:9]
.Lglb_pub_skip:
	s_waitcnt vmcnt(0)
	s_and_saveexec_b64 s[8:9], s[0:1]
	s_cbranch_execz .LBB0_1446
	v_mov_b32_e32 v6, s22
	v_mov_b32_e32 v7, s46
	ds_write_b32 v6, v7 offset:13308
	s_branch .LBB0_1446

; #define LAS __attribute__((address_space(3)))
; __device__ __forceinline__ f32x16 mma32(bf16x8 a, bf16x8 b, f32x16 c) { return __builtin_amdgcn_mfma_f32_32x32x16_bf16(a, b, c, 0, 0, 0); }
; __device__ __forceinline__ int acc_row(int reg, int hh) { return (reg & 3) + 8 * (reg >> 2) + 4 * hh; }
; #define LDS_WAIT() asm volatile("s_waitcnt lgkmcnt(0)" ::: "memory")
; __device__ __forceinline__ void gla_scan_task(const P& p, int l, int s, int h, int sl, LAS unsigned char* ldsw, int lane) {
;     ...
;         for (int ti = 0; ti < 2; ++ti) {
;             f32x16 o = zero16();
; #pragma unroll
;             for (int ks = 0; ks < 8; ++ks) { const bf16x8 b = *(const LAS bf16x8*)(ST + r * 136 + 16 * ks + 8 * hh); o = mma32(FRAG16(bufA, 4 + ti * 8 + ks, lane), b, o); }
; #pragma unroll
;             for (int ks = 0; ks < 4; ++ks) o = mma32(FRAG16(bufA, 20 + ti * 4 + ks, lane), vb[ks], o);
; #pragma unroll
;             for (int reg = 0; reg < 16; ++reg) p.OBRAW[(size_t)(r0 + 32 * ti + acc_row(reg, hh)) * 1024 + h * 256 + 32 * sl + r] = o[reg];
;         }
;         LDS_WAIT();
;         if (SCAN_LOADERS) { if (lane == 0) FL[3] = (unsigned)n + 1u; lds_wait_ge(FL + 2, (unsigned)n + 1u, FL + 5); }
.Lgp1_done:
	s_waitcnt lgkmcnt(0)
	ds_read_b128 v[236:239], v209 offset:28672
	ds_read_b128 v[240:243], v209 offset:29696
	ds_read_b128 v[244:247], v209 offset:30720
	ds_read_b128 v[168:171], v209 offset:31744
	ds_read_b128 v[212:215], v209 offset:32768
	ds_read_b128 v[216:219], v209 offset:33792
	s_waitcnt lgkmcnt(5)
	v_mfma_f32_32x32x16_bf16 v[66:81], v[236:239], v[122:125], 0
	ds_read_b128 v[220:223], v209 offset:34816
	s_waitcnt lgkmcnt(5)
	v_mfma_f32_32x32x16_bf16 v[66:81], v[240:243], v[118:121], v[66:81]
	ds_read_b128 v[224:227], v209 offset:35840
	s_waitcnt lgkmcnt(5)
	v_mfma_f32_32x32x16_bf16 v[66:81], v[244:247], v[126:129], v[66:81]
	ds_read_b128 v[228:231], v209 offset:40960
	s_waitcnt lgkmcnt(5)
	v_mfma_f32_32x32x16_bf16 v[66:81], v[168:171], v[114:117], v[66:81]
	ds_read_b128 v[232:235], v209 offset:41984
	s_waitcnt lgkmcnt(5)
	v_mfma_f32_32x32x16_bf16 v[66:81], v[212:215], v[110:113], v[66:81]
	ds_read_b128 v[236:239], v209 offset:43008
	s_waitcnt lgkmcnt(5)
	v_mfma_f32_32x32x16_bf16 v[66:81], v[216:219], v[106:109], v[66:81]
	ds_read_b128 v[240:243], v209 offset:44032
	s_waitcnt lgkmcnt(5)
	v_mfma_f32_32x32x16_bf16 v[66:81], v[220:223], v[102:105], v[66:81]
	s_waitcnt lgkmcnt(4)
	v_mfma_f32_32x32x16_bf16 v[66:81], v[224:227], v[98:101], v[66:81]
	s_waitcnt lgkmcnt(3)
	v_mfma_f32_32x32x16_bf16 v[66:81], v[228:231], v[94:97], v[66:81]
	s_waitcnt lgkmcnt(2)
	v_mfma_f32_32x32x16_bf16 v[66:81], v[232:235], v[90:93], v[66:81]
	s_waitcnt lgkmcnt(1)
	v_mfma_f32_32x32x16_bf16 v[66:81], v[236:239], v[86:89], v[66:81]
	s_waitcnt lgkmcnt(0)
	v_mfma_f32_32x32x16_bf16 v[66:81], v[240:243], v[82:85], v[66:81]
	s_and_saveexec_b64 s[8:9], s[0:1]
	v_mov_b32_e32 v255, s7
	ds_write_b32 v163, v255 offset:13324
	s_or_b64 exec, exec, s[8:9]
	s_nop 11
	v_subrev_u32_e32 v137, s100, v130
	v_lshl_add_u32 v136, v132, 12, v137
	v_add_u32_e32 v136, 0x21000, v136
	global_store_dword v136, v66, s[100:101] offset:-4096
	global_store_dword v136, v67, s[100:101]
	v_add_u32_e32 v136, 0x2000, v136
	global_store_dword v136, v68, s[100:101] offset:-4096
	global_store_dword v136, v69, s[100:101]
	v_add_u32_e32 v136, 0x6000, v136
	global_store_dword v136, v70, s[100:101] offset:-4096
	global_store_dword v136, v71, s[100:101]
	v_add_u32_e32 v136, 0x2000, v136
	global_store_dword v136, v72, s[100:101] offset:-4096
	global_store_dword v136, v73, s[100:101]
	v_add_u32_e32 v136, 0x6000, v136
	global_store_dword v136, v74, s[100:101] offset:-4096
	global_store_dword v136, v75, s[100:101]
	v_add_u32_e32 v136, 0x2000, v136
	global_store_dword v136, v76, s[100:101] offset:-4096
	global_store_dword v136, v77, s[100:101]
	v_add_u32_e32 v136, 0x6000, v136
	global_store_dword v136, v78, s[100:101] offset:-4096
	global_store_dword v136, v79, s[100:101]
	v_add_u32_e32 v136, 0x2000, v136
	global_store_dword v136, v80, s[100:101] offset:-4096
	global_store_dword v136, v81, s[100:101]
	s_waitcnt lgkmcnt(0)
	s_and_saveexec_b64 s[8:9], s[0:1]
	s_or_b64 exec, exec, s[8:9]
	ds_read_b32 v66, v163 offset:13344
	s_waitcnt lgkmcnt(0)
	v_cmp_lt_u32_e32 vcc, s34, v66
	s_cbranch_vccnz .LBB0_1556
	s_mov_b32 s4, 1
	s_branch .LBB0_1548

; #define LAS __attribute__((address_space(3)))
; template <bool SLEEP = false> __device__ __forceinline__ bool lds_wait_ge(volatile LAS unsigned* w, unsigned need, volatile LAS unsigned* abortw) {
;     unsigned sp = 0; bool ok = true;
;     while (*w < need) { if (SLEEP) __builtin_amdgcn_s_sleep(1); if ((++sp & 1023u) == 0u) { if (*abortw != 0u) { ok = false; break; } if (sp > (1u << 22)) { *abortw = 1u; ok = false; break; } } }
;     __builtin_amdgcn_fence(__ATOMIC_ACQUIRE, "workgroup");
.LBB0_1550:
	ds_read_b32 v66, v163 offset:13344
	s_add_i32 s4, s4, 1
	s_mov_b64 s[10:11], -1
	s_waitcnt lgkmcnt(0)
	v_cmp_lt_u32_e64 s[8:9], s34, v66
	s_branch .LBB0_1547

; __device__ __forceinline__ f32x16 mma32(bf16x8 a, bf16x8 b, f32x16 c) { return __builtin_amdgcn_mfma_f32_32x32x16_bf16(a, b, c, 0, 0, 0); }
; __device__ __forceinline__ void gla_scan_task(const P& p, int l, int s, int h, int sl, LAS unsigned char* ldsw, int lane) {
;     ...
; #pragma unroll
;         for (int d = 0; d < 4; ++d) {
; #pragma unroll
;             for (int ks = 0; ks < 4; ++ks) S[d] = mma32(FRAG16(bufB, d * 4 + ks, lane), vb[ks], S[d]);
; #pragma unroll
;             for (int g = 0; g < 4; ++g) { const f32x4v dc = FRAGF4(bufB, 16 + d * 4 + g, lane); S[d][4 * g] *= dc.x; S[d][4 * g + 1] *= dc.y; S[d][4 * g + 2] *= dc.z; S[d][4 * g + 3] *= dc.w; }
.LBB0_1556:
	s_waitcnt lgkmcnt(0)
	v_add_u32_e32 v173, 0xf000, v209
	ds_read_b128 v[236:239], v209 offset:45056
	ds_read_b128 v[240:243], v209 offset:46080
	ds_read_b128 v[244:247], v209 offset:47104
	ds_read_b128 v[168:171], v209 offset:48128
	ds_read_b128 v[212:215], v209 offset:49152
	ds_read_b128 v[216:219], v209 offset:50176
	s_waitcnt lgkmcnt(5)
	v_mfma_f32_32x32x16_bf16 v[50:65], v[236:239], v[94:97], v[50:65]
	ds_read_b128 v[220:223], v209 offset:51200
	s_waitcnt lgkmcnt(5)
	v_mfma_f32_32x32x16_bf16 v[50:65], v[240:243], v[90:93], v[50:65]
	ds_read_b128 v[224:227], v209 offset:52224
	s_waitcnt lgkmcnt(5)
	v_mfma_f32_32x32x16_bf16 v[50:65], v[244:247], v[86:89], v[50:65]
	s_mov_b32 s4, 0
.Lgb1_spin:
	ds_read_b32 v255, v163 offset:13320
	s_waitcnt lgkmcnt(0)
	v_cmp_lt_u32_e32 vcc, s34, v255
	s_cbranch_vccnz .Lgb1_go
	s_add_i32 s4, s4, 1
	s_cmp_lt_u32 s4, 0x400000
	s_cbranch_scc1 .Lgb1_spin
.Lgb1_go:
	ds_read_b128 v[228:231], v209 offset:53248
	s_waitcnt lgkmcnt(5)
	v_mfma_f32_32x32x16_bf16 v[50:65], v[168:171], v[82:85], v[50:65]
	ds_read_b128 v[98:101], v173 offset:0
	ds_read_b128 v[74:77], v173 offset:1024
	ds_read_b128 v[70:73], v173 offset:2048
	ds_read_b128 v[66:69], v173 offset:3072
	ds_read_b128 v[232:235], v209 offset:54272
	s_waitcnt lgkmcnt(9)
	v_mfma_f32_32x32x16_bf16 v[34:49], v[212:215], v[94:97], v[34:49]
	ds_read_b128 v[236:239], v209 offset:55296
	s_waitcnt lgkmcnt(9)
	v_mfma_f32_32x32x16_bf16 v[34:49], v[216:219], v[90:93], v[34:49]
	ds_read_b128 v[240:243], v209 offset:56320
	s_waitcnt lgkmcnt(9)
	v_mfma_f32_32x32x16_bf16 v[34:49], v[220:223], v[86:89], v[34:49]
	ds_read_b128 v[244:247], v209 offset:57344
	s_waitcnt lgkmcnt(9)
	v_mfma_f32_32x32x16_bf16 v[34:49], v[224:227], v[82:85], v[34:49]
	ds_read_b128 v[110:113], v173 offset:4096
	ds_read_b128 v[106:109], v173 offset:5120
	ds_read_b128 v[102:105], v173 offset:6144
	ds_read_b128 v[78:81], v173 offset:7168
	ds_read_b128 v[168:171], v209 offset:58368
	s_waitcnt lgkmcnt(13)
	v_mfma_f32_32x32x16_bf16 v[18:33], v[228:231], v[94:97], v[18:33]
	ds_read_b128 v[212:215], v209 offset:59392
	s_waitcnt lgkmcnt(9)
	v_mfma_f32_32x32x16_bf16 v[18:33], v[232:235], v[90:93], v[18:33]
	ds_read_b128 v[216:219], v209 offset:60416
	s_waitcnt lgkmcnt(9)
	v_mfma_f32_32x32x16_bf16 v[18:33], v[236:239], v[86:89], v[18:33]
	s_waitcnt lgkmcnt(8)
	v_mfma_f32_32x32x16_bf16 v[18:33], v[240:243], v[82:85], v[18:33]
	ds_read_b128 v[126:129], v173 offset:8192
	ds_read_b128 v[122:125], v173 offset:9216
	ds_read_b128 v[118:121], v173 offset:10240
	ds_read_b128 v[114:117], v173 offset:11264
	s_waitcnt lgkmcnt(11)
	v_mfma_f32_32x32x16_bf16 v[2:17], v[244:247], v[94:97], v[2:17]
	s_waitcnt lgkmcnt(6)
	v_mfma_f32_32x32x16_bf16 v[2:17], v[168:171], v[90:93], v[2:17]
	s_waitcnt lgkmcnt(5)
	v_mfma_f32_32x32x16_bf16 v[2:17], v[212:215], v[86:89], v[2:17]
	s_waitcnt lgkmcnt(4)
	v_mfma_f32_32x32x16_bf16 v[2:17], v[216:219], v[82:85], v[2:17]
	ds_read_b128 v[90:93], v173 offset:12288
	ds_read_b128 v[94:97], v173 offset:13312
	ds_read_b128 v[82:85], v173 offset:14336
	ds_read_b128 v[86:89], v173 offset:15360
	s_and_saveexec_b64 s[8:9], s[0:1]
	s_cbranch_execz .LBB0_1520
	v_mov_b32_e32 v132, s7
	ds_write_b32 v163, v132 offset:13328
	s_branch .LBB0_1520
